# grid barrier: non-leader workgroups poll the top-level generation word directly (one release hop fewer)
# speedup vs baseline: 1.0091x; 1.0091x over previous
.LBB0_181:
	s_or_b64 exec, exec, s[2:3]
	v_cvt_f32_u32_e32 v4, v2
	s_waitcnt vmcnt(0)
	v_readfirstlane_b32 s2, v3
	v_sub_u32_e32 v3, 0, v2
	v_rcp_iflag_f32_e32 v4, v4
	v_add_u32_e32 v5, s2, v1
	v_mul_f32_e32 v4, 0x4f7ffffe, v4
	v_cvt_u32_f32_e32 v4, v4
	v_mul_lo_u32 v1, v3, v4
	v_mul_hi_u32 v1, v4, v1
	v_add_u32_e32 v1, v4, v1
	v_mul_hi_u32 v1, v5, v1
	v_mul_lo_u32 v3, v1, v2
	v_sub_u32_e32 v3, v5, v3
	v_add_u32_e32 v4, 1, v1
	v_cmp_ge_u32_e32 vcc, v3, v2
	s_nop 1
	v_cndmask_b32_e32 v1, v1, v4, vcc
	v_sub_u32_e32 v4, v3, v2
	v_cndmask_b32_e32 v3, v3, v4, vcc
	v_add_u32_e32 v4, 1, v1
	v_cmp_ge_u32_e32 vcc, v3, v2
	v_add_u32_e32 v3, 1, v5
	s_nop 0
	v_cndmask_b32_e32 v1, v1, v4, vcc
	v_mul_lo_u32 v4, v2, v1
	v_add_u32_e32 v2, v4, v2
	v_cmp_ne_u32_e32 vcc, v3, v2
	s_and_saveexec_b64 s[2:3], vcc
	s_xor_b64 s[2:3], exec, s[2:3]
	s_cbranch_execz .LBB0_195
	v_readlane_b32 s4, v253, 31
	s_waitcnt lgkmcnt(0)
	v_mov_b32_e32 v0, 0
	v_readlane_b32 s5, v253, 32
	s_nop 4
	global_load_dword v2, v0, s[4:5] sc1
	s_waitcnt vmcnt(0)
	v_cmp_eq_u32_e32 vcc, v2, v1
	s_and_saveexec_b64 s[16:17], vcc
	s_cbranch_execz .LBB0_194
	s_mov_b32 s4, 1
	s_mov_b64 s[18:19], 0
	s_branch .LBB0_185

.LBB0_187:
	v_readlane_b32 s6, v253, 31
	v_readlane_b32 s7, v253, 32
	s_add_i32 s4, s4, 1
	s_mov_b64 s[42:43], -1
	s_nop 2
	global_load_dword v2, v0, s[6:7] sc1
	s_waitcnt vmcnt(0)
	v_cmp_ne_u32_e32 vcc, v2, v1
	s_orn2_b64 s[26:27], vcc, exec
	s_branch .LBB0_184

.LBB0_329:
	s_or_b64 exec, exec, s[2:3]
	v_cvt_f32_u32_e32 v4, v2
	s_waitcnt vmcnt(0)
	v_readfirstlane_b32 s2, v3
	v_sub_u32_e32 v3, 0, v2
	v_rcp_iflag_f32_e32 v4, v4
	v_add_u32_e32 v5, s2, v1
	v_mul_f32_e32 v4, 0x4f7ffffe, v4
	v_cvt_u32_f32_e32 v4, v4
	v_mul_lo_u32 v1, v3, v4
	v_mul_hi_u32 v1, v4, v1
	v_add_u32_e32 v1, v4, v1
	v_mul_hi_u32 v1, v5, v1
	v_mul_lo_u32 v3, v1, v2
	v_sub_u32_e32 v3, v5, v3
	v_add_u32_e32 v4, 1, v1
	v_cmp_ge_u32_e32 vcc, v3, v2
	s_nop 1
	v_cndmask_b32_e32 v1, v1, v4, vcc
	v_sub_u32_e32 v4, v3, v2
	v_cndmask_b32_e32 v3, v3, v4, vcc
	v_add_u32_e32 v4, 1, v1
	v_cmp_ge_u32_e32 vcc, v3, v2
	v_add_u32_e32 v3, 1, v5
	s_nop 0
	v_cndmask_b32_e32 v1, v1, v4, vcc
	v_mul_lo_u32 v4, v2, v1
	v_add_u32_e32 v2, v4, v2
	v_cmp_ne_u32_e32 vcc, v3, v2
	s_and_saveexec_b64 s[2:3], vcc
	s_xor_b64 s[2:3], exec, s[2:3]
	s_cbranch_execz .LBB0_343
	v_readlane_b32 s4, v253, 31
	v_readlane_b32 s5, v253, 32
	s_waitcnt lgkmcnt(0)
	s_nop 3
	global_load_dword v0, v129, s[4:5] sc1
	s_waitcnt vmcnt(0)
	v_cmp_eq_u32_e32 vcc, v0, v1
	s_and_saveexec_b64 s[18:19], vcc
	s_cbranch_execz .LBB0_342
	s_mov_b32 s4, 1
	s_mov_b64 s[42:43], 0
	s_branch .LBB0_333

.LBB0_335:
	v_readlane_b32 s6, v253, 31
	v_readlane_b32 s7, v253, 32
	s_add_i32 s4, s4, 1
	s_mov_b64 s[48:49], -1
	s_nop 2
	global_load_dword v0, v129, s[6:7] sc1
	s_waitcnt vmcnt(0)
	v_cmp_ne_u32_e32 vcc, v0, v1
	s_orn2_b64 s[46:47], vcc, exec
	s_branch .LBB0_332

.LBB0_635:
	s_or_b64 exec, exec, s[2:3]
	v_cvt_f32_u32_e32 v4, v2
	s_waitcnt vmcnt(0)
	v_readfirstlane_b32 s2, v3
	v_sub_u32_e32 v3, 0, v2
	v_rcp_iflag_f32_e32 v4, v4
	v_add_u32_e32 v5, s2, v1
	v_mul_f32_e32 v4, 0x4f7ffffe, v4
	v_cvt_u32_f32_e32 v4, v4
	v_mul_lo_u32 v1, v3, v4
	v_mul_hi_u32 v1, v4, v1
	v_add_u32_e32 v1, v4, v1
	v_mul_hi_u32 v1, v5, v1
	v_mul_lo_u32 v3, v1, v2
	v_sub_u32_e32 v3, v5, v3
	v_add_u32_e32 v4, 1, v1
	v_cmp_ge_u32_e32 vcc, v3, v2
	s_nop 1
	v_cndmask_b32_e32 v1, v1, v4, vcc
	v_sub_u32_e32 v4, v3, v2
	v_cndmask_b32_e32 v3, v3, v4, vcc
	v_add_u32_e32 v4, 1, v1
	v_cmp_ge_u32_e32 vcc, v3, v2
	v_add_u32_e32 v3, 1, v5
	s_nop 0
	v_cndmask_b32_e32 v1, v1, v4, vcc
	v_mul_lo_u32 v4, v2, v1
	v_add_u32_e32 v2, v4, v2
	v_cmp_ne_u32_e32 vcc, v3, v2
	s_and_saveexec_b64 s[2:3], vcc
	s_xor_b64 s[2:3], exec, s[2:3]
	s_cbranch_execz .LBB0_649
	v_readlane_b32 s8, v253, 31
	v_readlane_b32 s9, v253, 32
	s_waitcnt lgkmcnt(0)
	s_nop 3
	global_load_dword v0, v129, s[8:9] sc1
	s_waitcnt vmcnt(0)
	v_cmp_eq_u32_e32 vcc, v0, v1
	s_and_saveexec_b64 s[18:19], vcc
	s_cbranch_execz .LBB0_648
	s_mov_b32 s20, 1
	s_mov_b64 s[42:43], 0
	s_branch .LBB0_639

.LBB0_641:
	v_readlane_b32 s8, v253, 31
	v_readlane_b32 s9, v253, 32
	s_add_i32 s20, s20, 1
	s_mov_b64 s[50:51], -1
	s_nop 2
	global_load_dword v0, v129, s[8:9] sc1
	s_waitcnt vmcnt(0)
	v_cmp_ne_u32_e32 vcc, v0, v1
	s_orn2_b64 s[48:49], vcc, exec
	s_branch .LBB0_638

.LBB0_697:
	v_readlane_b32 s8, v253, 31
	v_readlane_b32 s9, v253, 32
	s_add_i32 s20, s20, 1
	s_mov_b64 s[48:49], -1
	s_nop 2
	global_load_dword v0, v129, s[8:9] sc1
	s_waitcnt vmcnt(0)
	v_cmp_ne_u32_e32 vcc, v0, v1
	s_orn2_b64 s[46:47], vcc, exec
	s_branch .LBB0_694

.LBB0_776:
	s_or_b64 exec, exec, s[2:3]
	v_cvt_f32_u32_e32 v4, v2
	s_waitcnt vmcnt(0)
	v_readfirstlane_b32 s2, v3
	v_sub_u32_e32 v3, 0, v2
	v_rcp_iflag_f32_e32 v4, v4
	v_add_u32_e32 v5, s2, v1
	v_mul_f32_e32 v4, 0x4f7ffffe, v4
	v_cvt_u32_f32_e32 v4, v4
	v_mul_lo_u32 v1, v3, v4
	v_mul_hi_u32 v1, v4, v1
	v_add_u32_e32 v1, v4, v1
	v_mul_hi_u32 v1, v5, v1
	v_mul_lo_u32 v3, v1, v2
	v_sub_u32_e32 v3, v5, v3
	v_add_u32_e32 v4, 1, v1
	v_cmp_ge_u32_e32 vcc, v3, v2
	s_nop 1
	v_cndmask_b32_e32 v1, v1, v4, vcc
	v_sub_u32_e32 v4, v3, v2
	v_cndmask_b32_e32 v3, v3, v4, vcc
	v_add_u32_e32 v4, 1, v1
	v_cmp_ge_u32_e32 vcc, v3, v2
	v_add_u32_e32 v3, 1, v5
	s_nop 0
	v_cndmask_b32_e32 v1, v1, v4, vcc
	v_mul_lo_u32 v4, v2, v1
	v_add_u32_e32 v2, v4, v2
	v_cmp_ne_u32_e32 vcc, v3, v2
	s_and_saveexec_b64 s[2:3], vcc
	s_xor_b64 s[2:3], exec, s[2:3]
	s_cbranch_execz .LBB0_790
	v_readlane_b32 s6, v253, 31
	v_readlane_b32 s7, v253, 32
	s_waitcnt lgkmcnt(0)
	s_nop 3
	global_load_dword v0, v129, s[6:7] sc1
	s_waitcnt vmcnt(0)
	v_cmp_eq_u32_e32 vcc, v0, v1
	s_and_saveexec_b64 s[18:19], vcc
	s_cbranch_execz .LBB0_789
	s_mov_b32 s6, 1
	s_mov_b64 s[42:43], 0
	s_branch .LBB0_780

.LBB0_782:
	v_readlane_b32 s8, v253, 31
	v_readlane_b32 s9, v253, 32
	s_add_i32 s6, s6, 1
	s_mov_b64 s[48:49], -1
	s_nop 2
	global_load_dword v0, v129, s[8:9] sc1
	s_waitcnt vmcnt(0)
	v_cmp_ne_u32_e32 vcc, v0, v1
	s_orn2_b64 s[46:47], vcc, exec
	s_branch .LBB0_779

.LBB0_1259:
	s_or_b64 exec, exec, s[2:3]
	v_cvt_f32_u32_e32 v4, v2
	s_waitcnt vmcnt(0)
	v_readfirstlane_b32 s2, v3
	v_sub_u32_e32 v3, 0, v2
	v_rcp_iflag_f32_e32 v4, v4
	v_add_u32_e32 v5, s2, v1
	v_mul_f32_e32 v4, 0x4f7ffffe, v4
	v_cvt_u32_f32_e32 v4, v4
	v_mul_lo_u32 v1, v3, v4
	v_mul_hi_u32 v1, v4, v1
	v_add_u32_e32 v1, v4, v1
	v_mul_hi_u32 v1, v5, v1
	v_mul_lo_u32 v3, v1, v2
	v_sub_u32_e32 v3, v5, v3
	v_add_u32_e32 v4, 1, v1
	v_cmp_ge_u32_e32 vcc, v3, v2
	s_nop 1
	v_cndmask_b32_e32 v1, v1, v4, vcc
	v_sub_u32_e32 v4, v3, v2
	v_cndmask_b32_e32 v3, v3, v4, vcc
	v_add_u32_e32 v4, 1, v1
	v_cmp_ge_u32_e32 vcc, v3, v2
	v_add_u32_e32 v3, 1, v5
	s_nop 0
	v_cndmask_b32_e32 v1, v1, v4, vcc
	v_mul_lo_u32 v4, v2, v1
	v_add_u32_e32 v2, v4, v2
	v_cmp_ne_u32_e32 vcc, v3, v2
	s_and_saveexec_b64 s[2:3], vcc
	s_xor_b64 s[2:3], exec, s[2:3]
	s_cbranch_execz .LBB0_1273
	v_readlane_b32 s4, v253, 31
	v_readlane_b32 s5, v253, 32
	s_waitcnt lgkmcnt(0)
	s_nop 3
	global_load_dword v0, v129, s[4:5] sc1
	s_waitcnt vmcnt(0)
	v_cmp_eq_u32_e32 vcc, v0, v1
	s_and_saveexec_b64 s[18:19], vcc
	s_cbranch_execz .LBB0_1272
	s_mov_b32 s4, 1
	s_mov_b64 s[44:45], 0
	s_branch .LBB0_1263

.LBB0_1265:
	v_readlane_b32 s6, v253, 31
	v_readlane_b32 s7, v253, 32
	s_add_i32 s4, s4, 1
	s_mov_b64 s[50:51], -1
	s_nop 2
	global_load_dword v0, v129, s[6:7] sc1
	s_waitcnt vmcnt(0)
	v_cmp_ne_u32_e32 vcc, v0, v1
	s_orn2_b64 s[48:49], vcc, exec
	s_branch .LBB0_1262

.LBB0_1722:
	v_readlane_b32 s6, v253, 31
	v_readlane_b32 s7, v253, 32
	s_add_i32 s4, s4, 1
	s_mov_b64 s[50:51], -1
	s_nop 2
	global_load_dword v0, v129, s[6:7] sc1
	s_waitcnt vmcnt(0)
	v_cmp_ne_u32_e32 vcc, v0, v1
	s_orn2_b64 s[46:47], vcc, exec
	s_branch .LBB0_1719

.LBB0_2325:
	s_or_b64 exec, exec, s[2:3]
	v_cvt_f32_u32_e32 v4, v2
	s_waitcnt vmcnt(0)
	v_readfirstlane_b32 s2, v3
	v_sub_u32_e32 v3, 0, v2
	v_rcp_iflag_f32_e32 v4, v4
	v_add_u32_e32 v5, s2, v1
	v_mul_f32_e32 v4, 0x4f7ffffe, v4
	v_cvt_u32_f32_e32 v4, v4
	v_mul_lo_u32 v1, v3, v4
	v_mul_hi_u32 v1, v4, v1
	v_add_u32_e32 v1, v4, v1
	v_mul_hi_u32 v1, v5, v1
	v_mul_lo_u32 v3, v1, v2
	v_sub_u32_e32 v3, v5, v3
	v_add_u32_e32 v4, 1, v1
	v_cmp_ge_u32_e32 vcc, v3, v2
	s_nop 1
	v_cndmask_b32_e32 v1, v1, v4, vcc
	v_sub_u32_e32 v4, v3, v2
	v_cndmask_b32_e32 v3, v3, v4, vcc
	v_add_u32_e32 v4, 1, v1
	v_cmp_ge_u32_e32 vcc, v3, v2
	v_add_u32_e32 v3, 1, v5
	s_nop 0
	v_cndmask_b32_e32 v1, v1, v4, vcc
	v_mul_lo_u32 v4, v2, v1
	v_add_u32_e32 v2, v4, v2
	v_cmp_ne_u32_e32 vcc, v3, v2
	s_and_saveexec_b64 s[2:3], vcc
	s_xor_b64 s[2:3], exec, s[2:3]
	s_cbranch_execz .LBB0_2339
	v_readlane_b32 s6, v253, 31
	v_readlane_b32 s7, v253, 32
	s_waitcnt lgkmcnt(0)
	s_nop 3
	global_load_dword v0, v129, s[6:7] sc1
	s_waitcnt vmcnt(0)
	v_cmp_eq_u32_e32 vcc, v0, v1
	s_and_saveexec_b64 s[18:19], vcc
	s_cbranch_execz .LBB0_2338
	s_mov_b32 s5, 1
	s_mov_b64 s[42:43], 0
	s_branch .LBB0_2329

.LBB0_2331:
	v_readlane_b32 s6, v253, 31
	v_readlane_b32 s7, v253, 32
	s_add_i32 s5, s5, 1
	s_mov_b64 s[48:49], -1
	s_nop 2
	global_load_dword v0, v129, s[6:7] sc1
	s_waitcnt vmcnt(0)
	v_cmp_ne_u32_e32 vcc, v0, v1
	s_orn2_b64 s[46:47], vcc, exec
	s_branch .LBB0_2328

.LBB0_2419:
	v_readlane_b32 s6, v253, 31
	v_readlane_b32 s7, v253, 32
	s_add_i32 s5, s5, 1
	s_mov_b64 s[50:51], -1
	s_nop 2
	global_load_dword v0, v129, s[6:7] sc1
	s_waitcnt vmcnt(0)
	v_cmp_ne_u32_e32 vcc, v0, v1
	s_orn2_b64 s[48:49], vcc, exec
	s_branch .LBB0_2416
